# grid barrier: every 8th arriver of an XCD starts an early L2 write-back (hint; the leader's write-back unchanged)
# baseline (speedup 1.0000x reference)
.Lxb1_follow:
	v_add_u32_e32 v12, -1, v10
	v_and_b32_e32 v12, 7, v12
	v_cmp_eq_u32_e32 vcc, 0, v12
	s_cbranch_vccz .LLxb1_nowb
	buffer_wbl2 sc1
